# v39 + kvproj row_rstd: 8 serialized loads issued together with one wait
# speedup vs baseline: 1.0175x; 1.0000x over previous
.LBB0_730:
	s_andn2_saveexec_b64 s[10:11], s[2:3]
	s_cbranch_execz .LBB0_750
	v_readlane_b32 s0, v235, 24
	v_add_u32_e32 v30, 0xffffe8f0, v4
	v_readlane_b32 s1, v235, 25
	v_lshrrev_b32_e32 v90, 2, v30
	s_waitcnt lgkmcnt(0)
	v_mov_b64_e32 v[0:1], s[0:1]
	s_mov_b32 s0, 0xea000
	v_mad_u64_u32 v[88:89], s[0:1], v90, s0, v[0:1]
	s_barrier
	v_mbcnt_lo_u32_b32 v0, -1, 0
	v_mbcnt_hi_u32_b32 v0, -1, v0
	v_mov_b32_e32 v3, v102
	v_or_b32_e32 v0, s93, v0
	s_nop 0
	v_ashrrev_i32_e32 v5, 1, v0
	v_and_b32_e32 v6, 1, v0
	v_mad_i64_i32 v[0:1], s[0:1], v5, s86, v[88:89]
	v_lshlrev_b32_e32 v2, 7, v6
	v_lshl_add_u64 v[2:3], v[0:1], 0, v[2:3]
	s_mov_b64 s[0:1], 0x1c00
	v_lshl_add_u64 v[0:1], v[2:3], 0, s[0:1]
	s_movk_i32 s0, 0x1000
	v_add_co_u32_e32 v2, vcc, s0, v2
	s_nop 1
	v_addc_co_u32_e32 v3, vcc, 0, v3, vcc
	global_load_dwordx4 v[8:11], v[2:3], off offset:3072
	global_load_dwordx4 v[188:191], v[0:1], off offset:16
	global_load_dwordx4 v[192:195], v[0:1], off offset:32
	global_load_dwordx4 v[196:199], v[0:1], off offset:48
	global_load_dwordx4 v[200:203], v[0:1], off offset:64
	global_load_dwordx4 v[204:207], v[0:1], off offset:80
	global_load_dwordx4 v[208:211], v[0:1], off offset:96
	global_load_dwordx4 v[212:215], v[0:1], off offset:112
	s_waitcnt vmcnt(0) lgkmcnt(0)
	v_and_b32_e32 v3, 0xffff0000, v8
	v_lshlrev_b32_e32 v2, 16, v8
	v_mul_f32_e32 v3, v3, v3
	v_and_b32_e32 v7, 0xffff0000, v9
	v_fmac_f32_e32 v3, v2, v2
	v_lshlrev_b32_e32 v2, 16, v9
	v_mul_f32_e32 v7, v7, v7
	v_fmac_f32_e32 v7, v2, v2
	v_add_f32_e32 v2, v3, v7
	v_and_b32_e32 v7, 0xffff0000, v10
	v_lshlrev_b32_e32 v3, 16, v10
	v_mul_f32_e32 v7, v7, v7
	v_fmac_f32_e32 v7, v3, v3
	v_add_f32_e32 v2, v2, v7
	v_lshlrev_b32_e32 v3, 16, v11
	v_and_b32_e32 v7, 0xffff0000, v11
	v_mul_f32_e32 v7, v7, v7
	v_fmac_f32_e32 v7, v3, v3
	v_add_f32_e32 v2, v2, v7
	v_and_b32_e32 v7, 0xffff0000, v188
	v_lshlrev_b32_e32 v3, 16, v188
	v_mul_f32_e32 v7, v7, v7
	v_fmac_f32_e32 v7, v3, v3
	v_add_f32_e32 v2, v2, v7
	v_and_b32_e32 v7, 0xffff0000, v189
	v_lshlrev_b32_e32 v3, 16, v189
	v_mul_f32_e32 v7, v7, v7
	v_fmac_f32_e32 v7, v3, v3
	v_add_f32_e32 v2, v2, v7
	v_and_b32_e32 v7, 0xffff0000, v190
	v_lshlrev_b32_e32 v3, 16, v190
	v_mul_f32_e32 v7, v7, v7
	v_fmac_f32_e32 v7, v3, v3
	v_add_f32_e32 v2, v2, v7
	v_lshlrev_b32_e32 v3, 16, v191
	v_and_b32_e32 v7, 0xffff0000, v191
	v_mul_f32_e32 v7, v7, v7
	v_fmac_f32_e32 v7, v3, v3
	v_add_f32_e32 v2, v2, v7
	v_and_b32_e32 v7, 0xffff0000, v192
	v_lshlrev_b32_e32 v3, 16, v192
	v_mul_f32_e32 v7, v7, v7
	v_fmac_f32_e32 v7, v3, v3
	v_add_f32_e32 v2, v2, v7
	v_and_b32_e32 v7, 0xffff0000, v193
	v_lshlrev_b32_e32 v3, 16, v193
	v_mul_f32_e32 v7, v7, v7
	v_fmac_f32_e32 v7, v3, v3
	v_add_f32_e32 v2, v2, v7
	v_and_b32_e32 v7, 0xffff0000, v194
	v_lshlrev_b32_e32 v3, 16, v194
	v_mul_f32_e32 v7, v7, v7
	v_fmac_f32_e32 v7, v3, v3
	v_add_f32_e32 v2, v2, v7
	v_lshlrev_b32_e32 v3, 16, v195
	v_and_b32_e32 v7, 0xffff0000, v195
	v_mul_f32_e32 v7, v7, v7
	v_fmac_f32_e32 v7, v3, v3
	v_add_f32_e32 v2, v2, v7
	v_and_b32_e32 v7, 0xffff0000, v196
	v_lshlrev_b32_e32 v3, 16, v196
	v_mul_f32_e32 v7, v7, v7
	v_fmac_f32_e32 v7, v3, v3
	v_add_f32_e32 v2, v2, v7
	v_and_b32_e32 v7, 0xffff0000, v197
	v_lshlrev_b32_e32 v3, 16, v197
	v_mul_f32_e32 v7, v7, v7
	v_fmac_f32_e32 v7, v3, v3
	v_add_f32_e32 v2, v2, v7
	v_and_b32_e32 v7, 0xffff0000, v198
	v_lshlrev_b32_e32 v3, 16, v198
	v_mul_f32_e32 v7, v7, v7
	v_fmac_f32_e32 v7, v3, v3
	v_add_f32_e32 v2, v2, v7
	v_lshlrev_b32_e32 v3, 16, v199
	v_and_b32_e32 v7, 0xffff0000, v199
	v_mul_f32_e32 v7, v7, v7
	v_fmac_f32_e32 v7, v3, v3
	v_add_f32_e32 v2, v2, v7
	v_and_b32_e32 v7, 0xffff0000, v200
	v_lshlrev_b32_e32 v3, 16, v200
	v_mul_f32_e32 v7, v7, v7
	v_fmac_f32_e32 v7, v3, v3
	v_add_f32_e32 v2, v2, v7
	v_and_b32_e32 v7, 0xffff0000, v201
	v_lshlrev_b32_e32 v3, 16, v201
	v_mul_f32_e32 v7, v7, v7
	v_fmac_f32_e32 v7, v3, v3
	v_add_f32_e32 v2, v2, v7
	v_and_b32_e32 v7, 0xffff0000, v202
	v_lshlrev_b32_e32 v3, 16, v202
	v_mul_f32_e32 v7, v7, v7
	v_fmac_f32_e32 v7, v3, v3
	v_add_f32_e32 v2, v2, v7
	v_lshlrev_b32_e32 v3, 16, v203
	v_and_b32_e32 v7, 0xffff0000, v203
	v_mul_f32_e32 v7, v7, v7
	v_fmac_f32_e32 v7, v3, v3
	v_add_f32_e32 v2, v2, v7
	v_and_b32_e32 v7, 0xffff0000, v204
	v_lshlrev_b32_e32 v3, 16, v204
	v_mul_f32_e32 v7, v7, v7
	v_fmac_f32_e32 v7, v3, v3
	v_add_f32_e32 v2, v2, v7
	v_and_b32_e32 v7, 0xffff0000, v205
	v_lshlrev_b32_e32 v3, 16, v205
	v_mul_f32_e32 v7, v7, v7
	v_fmac_f32_e32 v7, v3, v3
	v_add_f32_e32 v2, v2, v7
	v_and_b32_e32 v7, 0xffff0000, v206
	v_lshlrev_b32_e32 v3, 16, v206
	v_mul_f32_e32 v7, v7, v7
	v_fmac_f32_e32 v7, v3, v3
	v_add_f32_e32 v2, v2, v7
	v_lshlrev_b32_e32 v3, 16, v207
	v_and_b32_e32 v7, 0xffff0000, v207
	v_mul_f32_e32 v7, v7, v7
	v_fmac_f32_e32 v7, v3, v3
	v_add_f32_e32 v2, v2, v7
	v_and_b32_e32 v7, 0xffff0000, v208
	v_lshlrev_b32_e32 v3, 16, v208
	v_mul_f32_e32 v7, v7, v7
	v_fmac_f32_e32 v7, v3, v3
	v_add_f32_e32 v2, v2, v7
	v_and_b32_e32 v7, 0xffff0000, v209
	v_lshlrev_b32_e32 v3, 16, v209
	v_mul_f32_e32 v7, v7, v7
	v_fmac_f32_e32 v7, v3, v3
	v_add_f32_e32 v2, v2, v7
	v_and_b32_e32 v7, 0xffff0000, v210
	v_lshlrev_b32_e32 v3, 16, v210
	v_mul_f32_e32 v7, v7, v7
	v_fmac_f32_e32 v7, v3, v3
	v_add_f32_e32 v2, v2, v7
	v_and_b32_e32 v7, 0xffff0000, v211
	v_lshlrev_b32_e32 v3, 16, v211
	v_mul_f32_e32 v7, v7, v7
	v_fmac_f32_e32 v7, v3, v3
	v_add_f32_e32 v7, v2, v7
	v_lshlrev_b32_e32 v8, 16, v212
	v_and_b32_e32 v0, 0xffff0000, v212
	v_mul_f32_e32 v0, v0, v0
	v_fmac_f32_e32 v0, v8, v8
	v_add_f32_e32 v0, v7, v0
	v_lshlrev_b32_e32 v7, 16, v213
	v_and_b32_e32 v1, 0xffff0000, v213
	v_mul_f32_e32 v1, v1, v1
	v_fmac_f32_e32 v1, v7, v7
	v_add_f32_e32 v0, v0, v1
	v_lshlrev_b32_e32 v1, 16, v214
	v_and_b32_e32 v2, 0xffff0000, v214
	v_mul_f32_e32 v2, v2, v2
	v_fmac_f32_e32 v2, v1, v1
	v_add_f32_e32 v0, v0, v2
	v_and_b32_e32 v2, 0xffff0000, v215
	v_lshlrev_b32_e32 v1, 16, v215
	v_mul_f32_e32 v2, v2, v2
	v_fmac_f32_e32 v2, v1, v1
	v_add_f32_e32 v0, v0, v2
	v_and_b32_e32 v2, 64, v170
	v_xor_b32_e32 v1, 1, v170
	v_add_u32_e32 v2, 64, v2
	v_cmp_lt_i32_e32 vcc, v1, v2
	s_nop 1
	v_cndmask_b32_e32 v1, v170, v1, vcc
	v_lshlrev_b32_e32 v1, 2, v1
	ds_bpermute_b32 v1, v1, v0
	v_cmp_eq_u32_e32 vcc, 0, v6
	s_and_saveexec_b64 s[0:1], vcc
	s_cbranch_execz .LBB0_733
	s_waitcnt lgkmcnt(0)
	v_add_f32_e32 v0, v0, v1
	v_fmamk_f32 v0, v0, 0x3c000000, v137
	v_mul_f32_e32 v1, 0x4b800000, v0
	v_cmp_gt_f32_e32 vcc, s87, v0
	s_nop 1
	v_cndmask_b32_e32 v0, v0, v1, vcc
	v_rsq_f32_e32 v0, v0
	s_nop 0
	v_mul_f32_e32 v1, 0x45800000, v0
	v_cndmask_b32_e32 v0, v0, v1, vcc
	v_lshl_add_u32 v1, v5, 2, s92
	ds_write_b32 v1, v0 offset:36864

.LBB0_1725:
	s_andn2_saveexec_b64 s[0:1], s[2:3]
	s_cbranch_execz .LBB0_1745
	v_readlane_b32 s2, v235, 49
	v_add_u32_e32 v30, 0xffffe8f0, v4
	v_readlane_b32 s3, v235, 50
	v_lshrrev_b32_e32 v90, 2, v30
	s_waitcnt lgkmcnt(0)
	v_mov_b64_e32 v[0:1], s[2:3]
	s_mov_b32 s2, 0xea000
	v_mad_u64_u32 v[88:89], s[2:3], v90, s2, v[0:1]
	s_barrier
	v_mbcnt_lo_u32_b32 v0, -1, 0
	v_mbcnt_hi_u32_b32 v0, -1, v0
	v_readlane_b32 s2, v235, 53
	v_mov_b32_e32 v3, v102
	s_nop 0
	v_or_b32_e32 v0, s2, v0
	s_nop 0
	v_ashrrev_i32_e32 v5, 1, v0
	v_and_b32_e32 v6, 1, v0
	v_mad_i64_i32 v[0:1], s[2:3], v5, s88, v[88:89]
	v_lshlrev_b32_e32 v2, 7, v6
	v_lshl_add_u64 v[2:3], v[0:1], 0, v[2:3]
	s_mov_b64 s[2:3], 0x1c00
	v_lshl_add_u64 v[0:1], v[2:3], 0, s[2:3]
	s_movk_i32 s2, 0x1000
	v_add_co_u32_e32 v2, vcc, s2, v2
	s_nop 1
	v_addc_co_u32_e32 v3, vcc, 0, v3, vcc
	global_load_dwordx4 v[8:11], v[2:3], off offset:3072
	global_load_dwordx4 v[188:191], v[0:1], off offset:16
	global_load_dwordx4 v[192:195], v[0:1], off offset:32
	global_load_dwordx4 v[196:199], v[0:1], off offset:48
	global_load_dwordx4 v[200:203], v[0:1], off offset:64
	global_load_dwordx4 v[204:207], v[0:1], off offset:80
	global_load_dwordx4 v[208:211], v[0:1], off offset:96
	global_load_dwordx4 v[212:215], v[0:1], off offset:112
	s_waitcnt vmcnt(0) lgkmcnt(0)
	v_and_b32_e32 v3, 0xffff0000, v8
	v_lshlrev_b32_e32 v2, 16, v8
	v_mul_f32_e32 v3, v3, v3
	v_and_b32_e32 v7, 0xffff0000, v9
	v_fmac_f32_e32 v3, v2, v2
	v_lshlrev_b32_e32 v2, 16, v9
	v_mul_f32_e32 v7, v7, v7
	v_fmac_f32_e32 v7, v2, v2
	v_add_f32_e32 v2, v3, v7
	v_and_b32_e32 v7, 0xffff0000, v10
	v_lshlrev_b32_e32 v3, 16, v10
	v_mul_f32_e32 v7, v7, v7
	v_fmac_f32_e32 v7, v3, v3
	v_add_f32_e32 v2, v2, v7
	v_lshlrev_b32_e32 v3, 16, v11
	v_and_b32_e32 v7, 0xffff0000, v11
	v_mul_f32_e32 v7, v7, v7
	v_fmac_f32_e32 v7, v3, v3
	v_add_f32_e32 v2, v2, v7
	v_and_b32_e32 v7, 0xffff0000, v188
	v_lshlrev_b32_e32 v3, 16, v188
	v_mul_f32_e32 v7, v7, v7
	v_fmac_f32_e32 v7, v3, v3
	v_add_f32_e32 v2, v2, v7
	v_and_b32_e32 v7, 0xffff0000, v189
	v_lshlrev_b32_e32 v3, 16, v189
	v_mul_f32_e32 v7, v7, v7
	v_fmac_f32_e32 v7, v3, v3
	v_add_f32_e32 v2, v2, v7
	v_and_b32_e32 v7, 0xffff0000, v190
	v_lshlrev_b32_e32 v3, 16, v190
	v_mul_f32_e32 v7, v7, v7
	v_fmac_f32_e32 v7, v3, v3
	v_add_f32_e32 v2, v2, v7
	v_lshlrev_b32_e32 v3, 16, v191
	v_and_b32_e32 v7, 0xffff0000, v191
	v_mul_f32_e32 v7, v7, v7
	v_fmac_f32_e32 v7, v3, v3
	v_add_f32_e32 v2, v2, v7
	v_and_b32_e32 v7, 0xffff0000, v192
	v_lshlrev_b32_e32 v3, 16, v192
	v_mul_f32_e32 v7, v7, v7
	v_fmac_f32_e32 v7, v3, v3
	v_add_f32_e32 v2, v2, v7
	v_and_b32_e32 v7, 0xffff0000, v193
	v_lshlrev_b32_e32 v3, 16, v193
	v_mul_f32_e32 v7, v7, v7
	v_fmac_f32_e32 v7, v3, v3
	v_add_f32_e32 v2, v2, v7
	v_and_b32_e32 v7, 0xffff0000, v194
	v_lshlrev_b32_e32 v3, 16, v194
	v_mul_f32_e32 v7, v7, v7
	v_fmac_f32_e32 v7, v3, v3
	v_add_f32_e32 v2, v2, v7
	v_lshlrev_b32_e32 v3, 16, v195
	v_and_b32_e32 v7, 0xffff0000, v195
	v_mul_f32_e32 v7, v7, v7
	v_fmac_f32_e32 v7, v3, v3
	v_add_f32_e32 v2, v2, v7
	v_and_b32_e32 v7, 0xffff0000, v196
	v_lshlrev_b32_e32 v3, 16, v196
	v_mul_f32_e32 v7, v7, v7
	v_fmac_f32_e32 v7, v3, v3
	v_add_f32_e32 v2, v2, v7
	v_and_b32_e32 v7, 0xffff0000, v197
	v_lshlrev_b32_e32 v3, 16, v197
	v_mul_f32_e32 v7, v7, v7
	v_fmac_f32_e32 v7, v3, v3
	v_add_f32_e32 v2, v2, v7
	v_and_b32_e32 v7, 0xffff0000, v198
	v_lshlrev_b32_e32 v3, 16, v198
	v_mul_f32_e32 v7, v7, v7
	v_fmac_f32_e32 v7, v3, v3
	v_add_f32_e32 v2, v2, v7
	v_lshlrev_b32_e32 v3, 16, v199
	v_and_b32_e32 v7, 0xffff0000, v199
	v_mul_f32_e32 v7, v7, v7
	v_fmac_f32_e32 v7, v3, v3
	v_add_f32_e32 v2, v2, v7
	v_and_b32_e32 v7, 0xffff0000, v200
	v_lshlrev_b32_e32 v3, 16, v200
	v_mul_f32_e32 v7, v7, v7
	v_fmac_f32_e32 v7, v3, v3
	v_add_f32_e32 v2, v2, v7
	v_and_b32_e32 v7, 0xffff0000, v201
	v_lshlrev_b32_e32 v3, 16, v201
	v_mul_f32_e32 v7, v7, v7
	v_fmac_f32_e32 v7, v3, v3
	v_add_f32_e32 v2, v2, v7
	v_and_b32_e32 v7, 0xffff0000, v202
	v_lshlrev_b32_e32 v3, 16, v202
	v_mul_f32_e32 v7, v7, v7
	v_fmac_f32_e32 v7, v3, v3
	v_add_f32_e32 v2, v2, v7
	v_lshlrev_b32_e32 v3, 16, v203
	v_and_b32_e32 v7, 0xffff0000, v203
	v_mul_f32_e32 v7, v7, v7
	v_fmac_f32_e32 v7, v3, v3
	v_add_f32_e32 v2, v2, v7
	v_and_b32_e32 v7, 0xffff0000, v204
	v_lshlrev_b32_e32 v3, 16, v204
	v_mul_f32_e32 v7, v7, v7
	v_fmac_f32_e32 v7, v3, v3
	v_add_f32_e32 v2, v2, v7
	v_and_b32_e32 v7, 0xffff0000, v205
	v_lshlrev_b32_e32 v3, 16, v205
	v_mul_f32_e32 v7, v7, v7
	v_fmac_f32_e32 v7, v3, v3
	v_add_f32_e32 v2, v2, v7
	v_and_b32_e32 v7, 0xffff0000, v206
	v_lshlrev_b32_e32 v3, 16, v206
	v_mul_f32_e32 v7, v7, v7
	v_fmac_f32_e32 v7, v3, v3
	v_add_f32_e32 v2, v2, v7
	v_lshlrev_b32_e32 v3, 16, v207
	v_and_b32_e32 v7, 0xffff0000, v207
	v_mul_f32_e32 v7, v7, v7
	v_fmac_f32_e32 v7, v3, v3
	v_add_f32_e32 v2, v2, v7
	v_and_b32_e32 v7, 0xffff0000, v208
	v_lshlrev_b32_e32 v3, 16, v208
	v_mul_f32_e32 v7, v7, v7
	v_fmac_f32_e32 v7, v3, v3
	v_add_f32_e32 v2, v2, v7
	v_and_b32_e32 v7, 0xffff0000, v209
	v_lshlrev_b32_e32 v3, 16, v209
	v_mul_f32_e32 v7, v7, v7
	v_fmac_f32_e32 v7, v3, v3
	v_add_f32_e32 v2, v2, v7
	v_and_b32_e32 v7, 0xffff0000, v210
	v_lshlrev_b32_e32 v3, 16, v210
	v_mul_f32_e32 v7, v7, v7
	v_fmac_f32_e32 v7, v3, v3
	v_add_f32_e32 v2, v2, v7
	v_and_b32_e32 v7, 0xffff0000, v211
	v_lshlrev_b32_e32 v3, 16, v211
	v_mul_f32_e32 v7, v7, v7
	v_fmac_f32_e32 v7, v3, v3
	v_add_f32_e32 v7, v2, v7
	v_lshlrev_b32_e32 v8, 16, v212
	v_and_b32_e32 v0, 0xffff0000, v212
	v_mul_f32_e32 v0, v0, v0
	v_fmac_f32_e32 v0, v8, v8
	v_add_f32_e32 v0, v7, v0
	v_lshlrev_b32_e32 v7, 16, v213
	v_and_b32_e32 v1, 0xffff0000, v213
	v_mul_f32_e32 v1, v1, v1
	v_fmac_f32_e32 v1, v7, v7
	v_add_f32_e32 v0, v0, v1
	v_lshlrev_b32_e32 v1, 16, v214
	v_and_b32_e32 v2, 0xffff0000, v214
	v_mul_f32_e32 v2, v2, v2
	v_fmac_f32_e32 v2, v1, v1
	v_add_f32_e32 v0, v0, v2
	v_and_b32_e32 v2, 0xffff0000, v215
	v_lshlrev_b32_e32 v1, 16, v215
	v_mul_f32_e32 v2, v2, v2
	v_fmac_f32_e32 v2, v1, v1
	v_add_f32_e32 v0, v0, v2
	v_and_b32_e32 v2, 64, v170
	v_xor_b32_e32 v1, 1, v170
	v_add_u32_e32 v2, 64, v2
	v_cmp_lt_i32_e32 vcc, v1, v2
	s_nop 1
	v_cndmask_b32_e32 v1, v170, v1, vcc
	v_lshlrev_b32_e32 v1, 2, v1
	ds_bpermute_b32 v1, v1, v0
	v_cmp_eq_u32_e32 vcc, 0, v6
	s_and_saveexec_b64 s[2:3], vcc
	s_cbranch_execz .LBB0_1728
	s_waitcnt lgkmcnt(0)
	v_add_f32_e32 v0, v0, v1
	v_fmamk_f32 v0, v0, 0x3c000000, v137
	s_mov_b32 s4, 0x800000
	v_mul_f32_e32 v1, 0x4b800000, v0
	v_cmp_gt_f32_e32 vcc, s4, v0
	s_nop 1
	v_cndmask_b32_e32 v0, v0, v1, vcc
	v_rsq_f32_e32 v0, v0
	s_nop 0
	v_mul_f32_e32 v1, 0x45800000, v0
	v_cndmask_b32_e32 v0, v0, v1, vcc
	v_lshl_add_u32 v1, v5, 2, s92
	ds_write_b32 v1, v0 offset:36864
